# SwiGLU epilogue row-groups 1-7 rewritten: packed mul/add, two output pairs interleaved so hazard nops vanish (same operations, same rounding)
# speedup vs baseline: 1.0035x; 1.0035x over previous
.LBB0_114:
	v_mov_b32_e32 v143, v218
	s_lshl_b32 s17, s24, 8
	s_add_i32 s17, s17, s47
	v_and_or_b32 v142, v143, 15, s17
	s_lshl_b32 s17, s25, 7
	v_lshrrev_b32_e32 v143, 1, v143
	v_and_or_b32 v143, v143, 24, s17
	v_or_b32_e32 v148, s48, v143
	v_ashrrev_i32_e32 v143, 31, v142
	v_lshl_add_u64 v[144:145], v[142:143], 3, s[10:11]
	global_load_dwordx2 v[146:147], v[144:145], off
	global_load_dwordx2 v[158:159], v[144:145], off offset:128
	global_load_dwordx2 v[160:161], v[144:145], off offset:256
	global_load_dwordx2 v[162:163], v[144:145], off offset:384
	global_load_dwordx2 v[164:165], v[144:145], off offset:1024
	global_load_dwordx2 v[166:167], v[144:145], off offset:1152
	global_load_dwordx2 v[168:169], v[144:145], off offset:1280
	global_load_dwordx2 v[170:171], v[144:145], off offset:1408
	v_ashrrev_i32_e32 v149, 31, v148
	s_waitcnt vmcnt(0)
	v_ffbh_u32_e32 v143, v147
	v_min_u32_e32 v143, 32, v143
	v_lshlrev_b64 v[146:147], v143, v[146:147]
	v_min_u32_e32 v146, 1, v146
	v_or_b32_e32 v146, v147, v146
	v_cvt_f32_u32_e32 v146, v146
	v_sub_u32_e32 v143, 32, v143
	v_ldexp_f32 v143, v146, v143
	v_fmamk_f32 v143, v143, 0x31800000, v219
	v_cmp_gt_f32_e32 vcc, s86, v143
	v_mul_f32_e32 v146, 0x4b800000, v143
	s_nop 0
	v_cndmask_b32_e32 v143, v143, v146, vcc
	v_rsq_f32_e32 v143, v143
	s_nop 0
	v_mul_f32_e32 v146, 0x45800000, v143
	v_cndmask_b32_e32 v154, v143, v146, vcc
	v_pk_mul_f32 v[126:127], v[126:127], v[154:155] op_sel_hi:[1,0]
	v_pk_mul_f32 v[118:119], v[118:119], v[154:155] op_sel_hi:[1,0]
	v_mul_f32_e32 v143, 0xbfb8aa3b, v126
	v_exp_f32_e32 v143, v143
	v_pk_mul_f32 v[120:121], v[120:121], v[154:155] op_sel_hi:[1,0]
	v_pk_mul_f32 v[122:123], v[122:123], v[154:155] op_sel_hi:[1,0]
	v_pk_mul_f32 v[114:115], v[114:115], v[154:155] op_sel_hi:[1,0]
	v_add_f32_e32 v143, 1.0, v143
	v_rcp_f32_e32 v156, v143
	v_mul_f32_e32 v143, 0xbfb8aa3b, v127
	v_exp_f32_e32 v143, v143
	v_mov_b64_e32 v[146:147], s[8:9]
	v_pk_mul_f32 v[116:117], v[116:117], v[154:155] op_sel_hi:[1,0]
	v_mad_i64_i32 v[150:151], s[24:25], v142, s83, v[146:147]
	v_add_f32_e32 v143, 1.0, v143
	v_rcp_f32_e32 v157, v143
	s_nop 0
	v_pk_mul_f32 v[126:127], v[126:127], v[156:157]
	s_nop 0
	v_pk_mul_f32 v[118:119], v[118:119], v[126:127]
	v_pk_mul_f32 v[126:127], v[128:129], v[154:155] op_sel_hi:[1,0]
	v_cvt_pk_bf16_f32 v118, v118, v119
	v_mul_f32_e32 v128, 0xbfb8aa3b, v126
	v_mul_f32_e32 v129, 0xbfb8aa3b, v127
	v_exp_f32_e32 v128, v128
	v_exp_f32_e32 v129, v129
	v_add_f32_e32 v128, 1.0, v128
	v_add_f32_e32 v129, 1.0, v129
	v_rcp_f32_e32 v128, v128
	v_rcp_f32_e32 v129, v129
	s_nop 0
	v_pk_mul_f32 v[126:127], v[126:127], v[128:129]
	s_nop 0
	v_pk_mul_f32 v[120:121], v[120:121], v[126:127]
	v_mul_f32_e32 v126, 0xbfb8aa3b, v122
	v_mul_f32_e32 v127, 0xbfb8aa3b, v123
	v_exp_f32_e32 v126, v126
	v_exp_f32_e32 v127, v127
	v_cvt_pk_bf16_f32 v119, v120, v121
	v_add_f32_e32 v126, 1.0, v126
	v_add_f32_e32 v127, 1.0, v127
	v_rcp_f32_e32 v126, v126
	v_rcp_f32_e32 v127, v127
	s_nop 0
	v_pk_mul_f32 v[122:123], v[122:123], v[126:127]
	s_nop 0
	v_pk_mul_f32 v[122:123], v[114:115], v[122:123]
	v_pk_mul_f32 v[114:115], v[124:125], v[154:155] op_sel_hi:[1,0]
	v_cvt_pk_bf16_f32 v120, v122, v123
	v_mul_f32_e32 v124, 0xbfb8aa3b, v114
	v_mul_f32_e32 v125, 0xbfb8aa3b, v115
	v_exp_f32_e32 v124, v124
	v_exp_f32_e32 v125, v125
	v_add_f32_e32 v124, 1.0, v124
	v_add_f32_e32 v125, 1.0, v125
	v_rcp_f32_e32 v124, v124
	v_rcp_f32_e32 v125, v125
	s_nop 0
	v_pk_mul_f32 v[114:115], v[114:115], v[124:125]
	s_nop 0
	v_pk_mul_f32 v[116:117], v[116:117], v[114:115]
	v_lshlrev_b64 v[114:115], 1, v[148:149]
	v_lshl_add_u64 v[124:125], v[150:151], 0, v[114:115]
	v_cvt_pk_bf16_f32 v121, v116, v117
	global_store_dwordx4 v[124:125], v[118:121], off
	v_mov_b32_e32 v192, 0xbfb8aa3b
	v_ffbh_u32_e32 v180, v159
	v_min_u32_e32 v180, 32, v180
	v_lshlrev_b64 v[178:179], v180, v[158:159]
	v_min_u32_e32 v178, 1, v178
	v_or_b32_e32 v178, v179, v178
	v_cvt_f32_u32_e32 v178, v178
	v_sub_u32_e32 v179, 32, v180
	v_ldexp_f32 v178, v178, v179
	v_fmamk_f32 v178, v178, 0x31800000, v219
	v_cmp_gt_f32_e32 vcc, s86, v178
	v_mul_f32_e32 v179, 0x4b800000, v178
	s_nop 0
	v_cndmask_b32_e32 v178, v178, v179, vcc
	v_rsq_f32_e32 v178, v178
	v_or_b32_e32 v181, 16, v142
	v_mul_f32_e32 v179, 0x45800000, v178
	v_cndmask_b32_e32 v178, v178, v179, vcc
	v_mad_i64_i32 v[182:183], s[24:25], v181, s83, v[146:147]
	v_pk_mul_f32 v[110:111], v[110:111], v[178:179] op_sel_hi:[1,0]
	v_pk_mul_f32 v[112:113], v[112:113], v[178:179] op_sel_hi:[1,0]
	v_pk_mul_f32 v[106:107], v[106:107], v[178:179] op_sel_hi:[1,0]
	v_pk_mul_f32 v[108:109], v[108:109], v[178:179] op_sel_hi:[1,0]
	v_pk_mul_f32 v[102:103], v[102:103], v[178:179] op_sel_hi:[1,0]
	v_pk_mul_f32 v[104:105], v[104:105], v[178:179] op_sel_hi:[1,0]
	v_pk_mul_f32 v[98:99], v[98:99], v[178:179] op_sel_hi:[1,0]
	v_pk_mul_f32 v[100:101], v[100:101], v[178:179] op_sel_hi:[1,0]
	v_pk_mul_f32 v[188:189], v[110:111], v[192:193] op_sel_hi:[1,0]
	v_pk_mul_f32 v[190:191], v[112:113], v[192:193] op_sel_hi:[1,0]
	v_exp_f32_e32 v188, v188
	v_exp_f32_e32 v189, v189
	v_exp_f32_e32 v190, v190
	v_exp_f32_e32 v191, v191
	v_pk_add_f32 v[188:189], v[188:189], 1.0 op_sel_hi:[1,0]
	v_pk_add_f32 v[190:191], v[190:191], 1.0 op_sel_hi:[1,0]
	v_rcp_f32_e32 v188, v188
	v_rcp_f32_e32 v189, v189
	v_rcp_f32_e32 v190, v190
	v_rcp_f32_e32 v191, v191
	v_pk_mul_f32 v[110:111], v[110:111], v[188:189]
	v_pk_mul_f32 v[112:113], v[112:113], v[190:191]
	v_pk_mul_f32 v[102:103], v[102:103], v[110:111]
	v_pk_mul_f32 v[104:105], v[104:105], v[112:113]
	v_cvt_pk_bf16_f32 v184, v102, v103
	v_cvt_pk_bf16_f32 v185, v104, v105
	v_pk_mul_f32 v[188:189], v[106:107], v[192:193] op_sel_hi:[1,0]
	v_pk_mul_f32 v[190:191], v[108:109], v[192:193] op_sel_hi:[1,0]
	v_exp_f32_e32 v188, v188
	v_exp_f32_e32 v189, v189
	v_exp_f32_e32 v190, v190
	v_exp_f32_e32 v191, v191
	v_pk_add_f32 v[188:189], v[188:189], 1.0 op_sel_hi:[1,0]
	v_pk_add_f32 v[190:191], v[190:191], 1.0 op_sel_hi:[1,0]
	v_rcp_f32_e32 v188, v188
	v_rcp_f32_e32 v189, v189
	v_rcp_f32_e32 v190, v190
	v_rcp_f32_e32 v191, v191
	v_pk_mul_f32 v[106:107], v[106:107], v[188:189]
	v_pk_mul_f32 v[108:109], v[108:109], v[190:191]
	v_pk_mul_f32 v[98:99], v[98:99], v[106:107]
	v_pk_mul_f32 v[100:101], v[100:101], v[108:109]
	v_cvt_pk_bf16_f32 v186, v98, v99
	v_cvt_pk_bf16_f32 v187, v100, v101
	v_lshl_add_u64 v[182:183], v[182:183], 0, v[114:115]
	global_store_dwordx4 v[182:183], v[184:187], off
	v_ffbh_u32_e32 v180, v161
	v_min_u32_e32 v180, 32, v180
	v_lshlrev_b64 v[178:179], v180, v[160:161]
	v_min_u32_e32 v178, 1, v178
	v_or_b32_e32 v178, v179, v178
	v_cvt_f32_u32_e32 v178, v178
	v_sub_u32_e32 v179, 32, v180
	v_ldexp_f32 v178, v178, v179
	v_fmamk_f32 v178, v178, 0x31800000, v219
	v_cmp_gt_f32_e32 vcc, s86, v178
	v_mul_f32_e32 v179, 0x4b800000, v178
	s_nop 0
	v_cndmask_b32_e32 v178, v178, v179, vcc
	v_rsq_f32_e32 v178, v178
	v_or_b32_e32 v181, 32, v142
	v_mul_f32_e32 v179, 0x45800000, v178
	v_cndmask_b32_e32 v178, v178, v179, vcc
	v_mad_i64_i32 v[182:183], s[24:25], v181, s83, v[146:147]
	v_pk_mul_f32 v[94:95], v[94:95], v[178:179] op_sel_hi:[1,0]
	v_pk_mul_f32 v[96:97], v[96:97], v[178:179] op_sel_hi:[1,0]
	v_pk_mul_f32 v[90:91], v[90:91], v[178:179] op_sel_hi:[1,0]
	v_pk_mul_f32 v[92:93], v[92:93], v[178:179] op_sel_hi:[1,0]
	v_pk_mul_f32 v[86:87], v[86:87], v[178:179] op_sel_hi:[1,0]
	v_pk_mul_f32 v[88:89], v[88:89], v[178:179] op_sel_hi:[1,0]
	v_pk_mul_f32 v[82:83], v[82:83], v[178:179] op_sel_hi:[1,0]
	v_pk_mul_f32 v[84:85], v[84:85], v[178:179] op_sel_hi:[1,0]
	v_pk_mul_f32 v[188:189], v[94:95], v[192:193] op_sel_hi:[1,0]
	v_pk_mul_f32 v[190:191], v[96:97], v[192:193] op_sel_hi:[1,0]
	v_exp_f32_e32 v188, v188
	v_exp_f32_e32 v189, v189
	v_exp_f32_e32 v190, v190
	v_exp_f32_e32 v191, v191
	v_pk_add_f32 v[188:189], v[188:189], 1.0 op_sel_hi:[1,0]
	v_pk_add_f32 v[190:191], v[190:191], 1.0 op_sel_hi:[1,0]
	v_rcp_f32_e32 v188, v188
	v_rcp_f32_e32 v189, v189
	v_rcp_f32_e32 v190, v190
	v_rcp_f32_e32 v191, v191
	v_pk_mul_f32 v[94:95], v[94:95], v[188:189]
	v_pk_mul_f32 v[96:97], v[96:97], v[190:191]
	v_pk_mul_f32 v[86:87], v[86:87], v[94:95]
	v_pk_mul_f32 v[88:89], v[88:89], v[96:97]
	v_cvt_pk_bf16_f32 v184, v86, v87
	v_cvt_pk_bf16_f32 v185, v88, v89
	v_pk_mul_f32 v[188:189], v[90:91], v[192:193] op_sel_hi:[1,0]
	v_pk_mul_f32 v[190:191], v[92:93], v[192:193] op_sel_hi:[1,0]
	v_exp_f32_e32 v188, v188
	v_exp_f32_e32 v189, v189
	v_exp_f32_e32 v190, v190
	v_exp_f32_e32 v191, v191
	v_pk_add_f32 v[188:189], v[188:189], 1.0 op_sel_hi:[1,0]
	v_pk_add_f32 v[190:191], v[190:191], 1.0 op_sel_hi:[1,0]
	v_rcp_f32_e32 v188, v188
	v_rcp_f32_e32 v189, v189
	v_rcp_f32_e32 v190, v190
	v_rcp_f32_e32 v191, v191
	v_pk_mul_f32 v[90:91], v[90:91], v[188:189]
	v_pk_mul_f32 v[92:93], v[92:93], v[190:191]
	v_pk_mul_f32 v[82:83], v[82:83], v[90:91]
	v_pk_mul_f32 v[84:85], v[84:85], v[92:93]
	v_cvt_pk_bf16_f32 v186, v82, v83
	v_cvt_pk_bf16_f32 v187, v84, v85
	v_lshl_add_u64 v[182:183], v[182:183], 0, v[114:115]
	global_store_dwordx4 v[182:183], v[184:187], off
	v_ffbh_u32_e32 v180, v163
	v_min_u32_e32 v180, 32, v180
	v_lshlrev_b64 v[178:179], v180, v[162:163]
	v_min_u32_e32 v178, 1, v178
	v_or_b32_e32 v178, v179, v178
	v_cvt_f32_u32_e32 v178, v178
	v_sub_u32_e32 v179, 32, v180
	v_ldexp_f32 v178, v178, v179
	v_fmamk_f32 v178, v178, 0x31800000, v219
	v_cmp_gt_f32_e32 vcc, s86, v178
	v_mul_f32_e32 v179, 0x4b800000, v178
	s_nop 0
	v_cndmask_b32_e32 v178, v178, v179, vcc
	v_rsq_f32_e32 v178, v178
	v_or_b32_e32 v181, 48, v142
	v_mul_f32_e32 v179, 0x45800000, v178
	v_cndmask_b32_e32 v178, v178, v179, vcc
	v_mad_i64_i32 v[182:183], s[24:25], v181, s83, v[146:147]
	v_pk_mul_f32 v[78:79], v[78:79], v[178:179] op_sel_hi:[1,0]
	v_pk_mul_f32 v[80:81], v[80:81], v[178:179] op_sel_hi:[1,0]
	v_pk_mul_f32 v[74:75], v[74:75], v[178:179] op_sel_hi:[1,0]
	v_pk_mul_f32 v[76:77], v[76:77], v[178:179] op_sel_hi:[1,0]
	v_pk_mul_f32 v[70:71], v[70:71], v[178:179] op_sel_hi:[1,0]
	v_pk_mul_f32 v[72:73], v[72:73], v[178:179] op_sel_hi:[1,0]
	v_pk_mul_f32 v[66:67], v[66:67], v[178:179] op_sel_hi:[1,0]
	v_pk_mul_f32 v[68:69], v[68:69], v[178:179] op_sel_hi:[1,0]
	v_pk_mul_f32 v[188:189], v[78:79], v[192:193] op_sel_hi:[1,0]
	v_pk_mul_f32 v[190:191], v[80:81], v[192:193] op_sel_hi:[1,0]
	v_exp_f32_e32 v188, v188
	v_exp_f32_e32 v189, v189
	v_exp_f32_e32 v190, v190
	v_exp_f32_e32 v191, v191
	v_pk_add_f32 v[188:189], v[188:189], 1.0 op_sel_hi:[1,0]
	v_pk_add_f32 v[190:191], v[190:191], 1.0 op_sel_hi:[1,0]
	v_rcp_f32_e32 v188, v188
	v_rcp_f32_e32 v189, v189
	v_rcp_f32_e32 v190, v190
	v_rcp_f32_e32 v191, v191
	v_pk_mul_f32 v[78:79], v[78:79], v[188:189]
	v_pk_mul_f32 v[80:81], v[80:81], v[190:191]
	v_pk_mul_f32 v[70:71], v[70:71], v[78:79]
	v_pk_mul_f32 v[72:73], v[72:73], v[80:81]
	v_cvt_pk_bf16_f32 v184, v70, v71
	v_cvt_pk_bf16_f32 v185, v72, v73
	v_pk_mul_f32 v[188:189], v[74:75], v[192:193] op_sel_hi:[1,0]
	v_pk_mul_f32 v[190:191], v[76:77], v[192:193] op_sel_hi:[1,0]
	v_exp_f32_e32 v188, v188
	v_exp_f32_e32 v189, v189
	v_exp_f32_e32 v190, v190
	v_exp_f32_e32 v191, v191
	v_pk_add_f32 v[188:189], v[188:189], 1.0 op_sel_hi:[1,0]
	v_pk_add_f32 v[190:191], v[190:191], 1.0 op_sel_hi:[1,0]
	v_rcp_f32_e32 v188, v188
	v_rcp_f32_e32 v189, v189
	v_rcp_f32_e32 v190, v190
	v_rcp_f32_e32 v191, v191
	v_pk_mul_f32 v[74:75], v[74:75], v[188:189]
	v_pk_mul_f32 v[76:77], v[76:77], v[190:191]
	v_pk_mul_f32 v[66:67], v[66:67], v[74:75]
	v_pk_mul_f32 v[68:69], v[68:69], v[76:77]
	v_cvt_pk_bf16_f32 v186, v66, v67
	v_cvt_pk_bf16_f32 v187, v68, v69
	v_lshl_add_u64 v[182:183], v[182:183], 0, v[114:115]
	global_store_dwordx4 v[182:183], v[184:187], off
	v_ffbh_u32_e32 v180, v165
	v_min_u32_e32 v180, 32, v180
	v_lshlrev_b64 v[178:179], v180, v[164:165]
	v_min_u32_e32 v178, 1, v178
	v_or_b32_e32 v178, v179, v178
	v_cvt_f32_u32_e32 v178, v178
	v_sub_u32_e32 v179, 32, v180
	v_ldexp_f32 v178, v178, v179
	v_fmamk_f32 v178, v178, 0x31800000, v219
	v_cmp_gt_f32_e32 vcc, s86, v178
	v_mul_f32_e32 v179, 0x4b800000, v178
	s_nop 0
	v_cndmask_b32_e32 v178, v178, v179, vcc
	v_rsq_f32_e32 v178, v178
	v_add_u32_e32 v181, 0x80, v142
	v_mul_f32_e32 v179, 0x45800000, v178
	v_cndmask_b32_e32 v178, v178, v179, vcc
	v_mad_i64_i32 v[182:183], s[24:25], v181, s83, v[146:147]
	v_pk_mul_f32 v[62:63], v[62:63], v[178:179] op_sel_hi:[1,0]
	v_pk_mul_f32 v[64:65], v[64:65], v[178:179] op_sel_hi:[1,0]
	v_pk_mul_f32 v[58:59], v[58:59], v[178:179] op_sel_hi:[1,0]
	v_pk_mul_f32 v[60:61], v[60:61], v[178:179] op_sel_hi:[1,0]
	v_pk_mul_f32 v[54:55], v[54:55], v[178:179] op_sel_hi:[1,0]
	v_pk_mul_f32 v[56:57], v[56:57], v[178:179] op_sel_hi:[1,0]
	v_pk_mul_f32 v[50:51], v[50:51], v[178:179] op_sel_hi:[1,0]
	v_pk_mul_f32 v[52:53], v[52:53], v[178:179] op_sel_hi:[1,0]
	v_pk_mul_f32 v[188:189], v[62:63], v[192:193] op_sel_hi:[1,0]
	v_pk_mul_f32 v[190:191], v[64:65], v[192:193] op_sel_hi:[1,0]
	v_exp_f32_e32 v188, v188
	v_exp_f32_e32 v189, v189
	v_exp_f32_e32 v190, v190
	v_exp_f32_e32 v191, v191
	v_pk_add_f32 v[188:189], v[188:189], 1.0 op_sel_hi:[1,0]
	v_pk_add_f32 v[190:191], v[190:191], 1.0 op_sel_hi:[1,0]
	v_rcp_f32_e32 v188, v188
	v_rcp_f32_e32 v189, v189
	v_rcp_f32_e32 v190, v190
	v_rcp_f32_e32 v191, v191
	v_pk_mul_f32 v[62:63], v[62:63], v[188:189]
	v_pk_mul_f32 v[64:65], v[64:65], v[190:191]
	v_pk_mul_f32 v[54:55], v[54:55], v[62:63]
	v_pk_mul_f32 v[56:57], v[56:57], v[64:65]
	v_cvt_pk_bf16_f32 v184, v54, v55
	v_cvt_pk_bf16_f32 v185, v56, v57
	v_pk_mul_f32 v[188:189], v[58:59], v[192:193] op_sel_hi:[1,0]
	v_pk_mul_f32 v[190:191], v[60:61], v[192:193] op_sel_hi:[1,0]
	v_exp_f32_e32 v188, v188
	v_exp_f32_e32 v189, v189
	v_exp_f32_e32 v190, v190
	v_exp_f32_e32 v191, v191
	v_pk_add_f32 v[188:189], v[188:189], 1.0 op_sel_hi:[1,0]
	v_pk_add_f32 v[190:191], v[190:191], 1.0 op_sel_hi:[1,0]
	v_rcp_f32_e32 v188, v188
	v_rcp_f32_e32 v189, v189
	v_rcp_f32_e32 v190, v190
	v_rcp_f32_e32 v191, v191
	v_pk_mul_f32 v[58:59], v[58:59], v[188:189]
	v_pk_mul_f32 v[60:61], v[60:61], v[190:191]
	v_pk_mul_f32 v[50:51], v[50:51], v[58:59]
	v_pk_mul_f32 v[52:53], v[52:53], v[60:61]
	v_cvt_pk_bf16_f32 v186, v50, v51
	v_cvt_pk_bf16_f32 v187, v52, v53
	v_lshl_add_u64 v[182:183], v[182:183], 0, v[114:115]
	global_store_dwordx4 v[182:183], v[184:187], off
	v_ffbh_u32_e32 v180, v167
	v_min_u32_e32 v180, 32, v180
	v_lshlrev_b64 v[178:179], v180, v[166:167]
	v_min_u32_e32 v178, 1, v178
	v_or_b32_e32 v178, v179, v178
	v_cvt_f32_u32_e32 v178, v178
	v_sub_u32_e32 v179, 32, v180
	v_ldexp_f32 v178, v178, v179
	v_fmamk_f32 v178, v178, 0x31800000, v219
	v_cmp_gt_f32_e32 vcc, s86, v178
	v_mul_f32_e32 v179, 0x4b800000, v178
	s_nop 0
	v_cndmask_b32_e32 v178, v178, v179, vcc
	v_rsq_f32_e32 v178, v178
	v_add_u32_e32 v181, 0x90, v142
	v_mul_f32_e32 v179, 0x45800000, v178
	v_cndmask_b32_e32 v178, v178, v179, vcc
	v_mad_i64_i32 v[182:183], s[24:25], v181, s83, v[146:147]
	v_pk_mul_f32 v[46:47], v[46:47], v[178:179] op_sel_hi:[1,0]
	v_pk_mul_f32 v[48:49], v[48:49], v[178:179] op_sel_hi:[1,0]
	v_pk_mul_f32 v[42:43], v[42:43], v[178:179] op_sel_hi:[1,0]
	v_pk_mul_f32 v[44:45], v[44:45], v[178:179] op_sel_hi:[1,0]
	v_pk_mul_f32 v[38:39], v[38:39], v[178:179] op_sel_hi:[1,0]
	v_pk_mul_f32 v[40:41], v[40:41], v[178:179] op_sel_hi:[1,0]
	v_pk_mul_f32 v[34:35], v[34:35], v[178:179] op_sel_hi:[1,0]
	v_pk_mul_f32 v[36:37], v[36:37], v[178:179] op_sel_hi:[1,0]
	v_pk_mul_f32 v[188:189], v[46:47], v[192:193] op_sel_hi:[1,0]
	v_pk_mul_f32 v[190:191], v[48:49], v[192:193] op_sel_hi:[1,0]
	v_exp_f32_e32 v188, v188
	v_exp_f32_e32 v189, v189
	v_exp_f32_e32 v190, v190
	v_exp_f32_e32 v191, v191
	v_pk_add_f32 v[188:189], v[188:189], 1.0 op_sel_hi:[1,0]
	v_pk_add_f32 v[190:191], v[190:191], 1.0 op_sel_hi:[1,0]
	v_rcp_f32_e32 v188, v188
	v_rcp_f32_e32 v189, v189
	v_rcp_f32_e32 v190, v190
	v_rcp_f32_e32 v191, v191
	v_pk_mul_f32 v[46:47], v[46:47], v[188:189]
	v_pk_mul_f32 v[48:49], v[48:49], v[190:191]
	v_pk_mul_f32 v[38:39], v[38:39], v[46:47]
	v_pk_mul_f32 v[40:41], v[40:41], v[48:49]
	v_cvt_pk_bf16_f32 v184, v38, v39
	v_cvt_pk_bf16_f32 v185, v40, v41
	v_pk_mul_f32 v[188:189], v[42:43], v[192:193] op_sel_hi:[1,0]
	v_pk_mul_f32 v[190:191], v[44:45], v[192:193] op_sel_hi:[1,0]
	v_exp_f32_e32 v188, v188
	v_exp_f32_e32 v189, v189
	v_exp_f32_e32 v190, v190
	v_exp_f32_e32 v191, v191
	v_pk_add_f32 v[188:189], v[188:189], 1.0 op_sel_hi:[1,0]
	v_pk_add_f32 v[190:191], v[190:191], 1.0 op_sel_hi:[1,0]
	v_rcp_f32_e32 v188, v188
	v_rcp_f32_e32 v189, v189
	v_rcp_f32_e32 v190, v190
	v_rcp_f32_e32 v191, v191
	v_pk_mul_f32 v[42:43], v[42:43], v[188:189]
	v_pk_mul_f32 v[44:45], v[44:45], v[190:191]
	v_pk_mul_f32 v[34:35], v[34:35], v[42:43]
	v_pk_mul_f32 v[36:37], v[36:37], v[44:45]
	v_cvt_pk_bf16_f32 v186, v34, v35
	v_cvt_pk_bf16_f32 v187, v36, v37
	v_lshl_add_u64 v[182:183], v[182:183], 0, v[114:115]
	global_store_dwordx4 v[182:183], v[184:187], off
	v_ffbh_u32_e32 v180, v169
	v_min_u32_e32 v180, 32, v180
	v_lshlrev_b64 v[178:179], v180, v[168:169]
	v_min_u32_e32 v178, 1, v178
	v_or_b32_e32 v178, v179, v178
	v_cvt_f32_u32_e32 v178, v178
	v_sub_u32_e32 v179, 32, v180
	v_ldexp_f32 v178, v178, v179
	v_fmamk_f32 v178, v178, 0x31800000, v219
	v_cmp_gt_f32_e32 vcc, s86, v178
	v_mul_f32_e32 v179, 0x4b800000, v178
	s_nop 0
	v_cndmask_b32_e32 v178, v178, v179, vcc
	v_rsq_f32_e32 v178, v178
	v_add_u32_e32 v181, 0xa0, v142
	v_mul_f32_e32 v179, 0x45800000, v178
	v_cndmask_b32_e32 v178, v178, v179, vcc
	v_mad_i64_i32 v[182:183], s[24:25], v181, s83, v[146:147]
	v_pk_mul_f32 v[30:31], v[30:31], v[178:179] op_sel_hi:[1,0]
	v_pk_mul_f32 v[32:33], v[32:33], v[178:179] op_sel_hi:[1,0]
	v_pk_mul_f32 v[26:27], v[26:27], v[178:179] op_sel_hi:[1,0]
	v_pk_mul_f32 v[28:29], v[28:29], v[178:179] op_sel_hi:[1,0]
	v_pk_mul_f32 v[22:23], v[22:23], v[178:179] op_sel_hi:[1,0]
	v_pk_mul_f32 v[24:25], v[24:25], v[178:179] op_sel_hi:[1,0]
	v_pk_mul_f32 v[18:19], v[18:19], v[178:179] op_sel_hi:[1,0]
	v_pk_mul_f32 v[20:21], v[20:21], v[178:179] op_sel_hi:[1,0]
	v_pk_mul_f32 v[188:189], v[30:31], v[192:193] op_sel_hi:[1,0]
	v_pk_mul_f32 v[190:191], v[32:33], v[192:193] op_sel_hi:[1,0]
	v_exp_f32_e32 v188, v188
	v_exp_f32_e32 v189, v189
	v_exp_f32_e32 v190, v190
	v_exp_f32_e32 v191, v191
	v_pk_add_f32 v[188:189], v[188:189], 1.0 op_sel_hi:[1,0]
	v_pk_add_f32 v[190:191], v[190:191], 1.0 op_sel_hi:[1,0]
	v_rcp_f32_e32 v188, v188
	v_rcp_f32_e32 v189, v189
	v_rcp_f32_e32 v190, v190
	v_rcp_f32_e32 v191, v191
	v_pk_mul_f32 v[30:31], v[30:31], v[188:189]
	v_pk_mul_f32 v[32:33], v[32:33], v[190:191]
	v_pk_mul_f32 v[22:23], v[22:23], v[30:31]
	v_pk_mul_f32 v[24:25], v[24:25], v[32:33]
	v_cvt_pk_bf16_f32 v184, v22, v23
	v_cvt_pk_bf16_f32 v185, v24, v25
	v_pk_mul_f32 v[188:189], v[26:27], v[192:193] op_sel_hi:[1,0]
	v_pk_mul_f32 v[190:191], v[28:29], v[192:193] op_sel_hi:[1,0]
	v_exp_f32_e32 v188, v188
	v_exp_f32_e32 v189, v189
	v_exp_f32_e32 v190, v190
	v_exp_f32_e32 v191, v191
	v_pk_add_f32 v[188:189], v[188:189], 1.0 op_sel_hi:[1,0]
	v_pk_add_f32 v[190:191], v[190:191], 1.0 op_sel_hi:[1,0]
	v_rcp_f32_e32 v188, v188
	v_rcp_f32_e32 v189, v189
	v_rcp_f32_e32 v190, v190
	v_rcp_f32_e32 v191, v191
	v_pk_mul_f32 v[26:27], v[26:27], v[188:189]
	v_pk_mul_f32 v[28:29], v[28:29], v[190:191]
	v_pk_mul_f32 v[18:19], v[18:19], v[26:27]
	v_pk_mul_f32 v[20:21], v[20:21], v[28:29]
	v_cvt_pk_bf16_f32 v186, v18, v19
	v_cvt_pk_bf16_f32 v187, v20, v21
	v_lshl_add_u64 v[182:183], v[182:183], 0, v[114:115]
	global_store_dwordx4 v[182:183], v[184:187], off
	v_ffbh_u32_e32 v180, v171
	v_min_u32_e32 v180, 32, v180
	v_lshlrev_b64 v[178:179], v180, v[170:171]
	v_min_u32_e32 v178, 1, v178
	v_or_b32_e32 v178, v179, v178
	v_cvt_f32_u32_e32 v178, v178
	v_sub_u32_e32 v179, 32, v180
	v_ldexp_f32 v178, v178, v179
	v_fmamk_f32 v178, v178, 0x31800000, v219
	v_cmp_gt_f32_e32 vcc, s86, v178
	v_mul_f32_e32 v179, 0x4b800000, v178
	s_nop 0
	v_cndmask_b32_e32 v178, v178, v179, vcc
	v_rsq_f32_e32 v178, v178
	v_add_u32_e32 v181, 0xb0, v142
	v_mul_f32_e32 v179, 0x45800000, v178
	v_cndmask_b32_e32 v178, v178, v179, vcc
	v_mad_i64_i32 v[182:183], s[24:25], v181, s83, v[146:147]
	s_andn2_b64 vcc, exec, s[2:3]
	v_pk_mul_f32 v[14:15], v[14:15], v[178:179] op_sel_hi:[1,0]
	v_pk_mul_f32 v[16:17], v[16:17], v[178:179] op_sel_hi:[1,0]
	v_pk_mul_f32 v[10:11], v[10:11], v[178:179] op_sel_hi:[1,0]
	v_pk_mul_f32 v[12:13], v[12:13], v[178:179] op_sel_hi:[1,0]
	v_pk_mul_f32 v[6:7], v[6:7], v[178:179] op_sel_hi:[1,0]
	v_pk_mul_f32 v[8:9], v[8:9], v[178:179] op_sel_hi:[1,0]
	v_pk_mul_f32 v[2:3], v[2:3], v[178:179] op_sel_hi:[1,0]
	v_pk_mul_f32 v[4:5], v[4:5], v[178:179] op_sel_hi:[1,0]
	s_mov_b64 s[24:25], -1
	v_pk_mul_f32 v[188:189], v[14:15], v[192:193] op_sel_hi:[1,0]
	v_pk_mul_f32 v[190:191], v[16:17], v[192:193] op_sel_hi:[1,0]
	v_exp_f32_e32 v188, v188
	v_exp_f32_e32 v189, v189
	v_exp_f32_e32 v190, v190
	v_exp_f32_e32 v191, v191
	v_pk_add_f32 v[188:189], v[188:189], 1.0 op_sel_hi:[1,0]
	v_pk_add_f32 v[190:191], v[190:191], 1.0 op_sel_hi:[1,0]
	v_rcp_f32_e32 v188, v188
	v_rcp_f32_e32 v189, v189
	v_rcp_f32_e32 v190, v190
	v_rcp_f32_e32 v191, v191
	v_pk_mul_f32 v[14:15], v[14:15], v[188:189]
	v_pk_mul_f32 v[16:17], v[16:17], v[190:191]
	v_pk_mul_f32 v[6:7], v[6:7], v[14:15]
	v_pk_mul_f32 v[8:9], v[8:9], v[16:17]
	v_cvt_pk_bf16_f32 v184, v6, v7
	v_cvt_pk_bf16_f32 v185, v8, v9
	v_pk_mul_f32 v[188:189], v[10:11], v[192:193] op_sel_hi:[1,0]
	v_pk_mul_f32 v[190:191], v[12:13], v[192:193] op_sel_hi:[1,0]
	v_exp_f32_e32 v188, v188
	v_exp_f32_e32 v189, v189
	v_exp_f32_e32 v190, v190
	v_exp_f32_e32 v191, v191
	v_pk_add_f32 v[188:189], v[188:189], 1.0 op_sel_hi:[1,0]
	v_pk_add_f32 v[190:191], v[190:191], 1.0 op_sel_hi:[1,0]
	v_rcp_f32_e32 v188, v188
	v_rcp_f32_e32 v189, v189
	v_rcp_f32_e32 v190, v190
	v_rcp_f32_e32 v191, v191
	v_pk_mul_f32 v[10:11], v[10:11], v[188:189]
	v_pk_mul_f32 v[12:13], v[12:13], v[190:191]
	v_pk_mul_f32 v[2:3], v[2:3], v[10:11]
	v_pk_mul_f32 v[4:5], v[4:5], v[12:13]
	v_cvt_pk_bf16_f32 v186, v2, v3
	v_cvt_pk_bf16_f32 v187, v4, v5
	v_lshl_add_u64 v[182:183], v[182:183], 0, v[114:115]
	global_store_dwordx4 v[182:183], v[184:187], off
	s_cbranch_vccnz .LBB0_107
	s_andn2_b64 vcc, exec, s[6:7]
	s_cbranch_vccnz .LBB0_106
	s_barrier
	s_branch .LBB0_106

.Lsw_skip_ffn2up:
	v_ashrrev_i32_e32 v149, 31, v148
	s_waitcnt vmcnt(0)
	v_ffbh_u32_e32 v143, v147
	v_min_u32_e32 v143, 32, v143
	v_lshlrev_b64 v[146:147], v143, v[146:147]
	v_min_u32_e32 v146, 1, v146
	v_or_b32_e32 v146, v147, v146
	v_cvt_f32_u32_e32 v146, v146
	v_sub_u32_e32 v143, 32, v143
	v_ldexp_f32 v143, v146, v143
	v_fmamk_f32 v143, v143, 0x31800000, v219
	v_cmp_gt_f32_e32 vcc, s86, v143
	v_mul_f32_e32 v146, 0x4b800000, v143
	s_nop 0
	v_cndmask_b32_e32 v143, v143, v146, vcc
	v_rsq_f32_e32 v143, v143
	s_nop 0
	v_mul_f32_e32 v146, 0x45800000, v143
	v_cndmask_b32_e32 v154, v143, v146, vcc
	v_pk_mul_f32 v[126:127], v[126:127], v[154:155] op_sel_hi:[1,0]
	v_pk_mul_f32 v[118:119], v[118:119], v[154:155] op_sel_hi:[1,0]
	v_mul_f32_e32 v143, 0xbfb8aa3b, v126
	v_exp_f32_e32 v143, v143
	v_pk_mul_f32 v[120:121], v[120:121], v[154:155] op_sel_hi:[1,0]
	v_pk_mul_f32 v[122:123], v[122:123], v[154:155] op_sel_hi:[1,0]
	v_pk_mul_f32 v[114:115], v[114:115], v[154:155] op_sel_hi:[1,0]
	v_add_f32_e32 v143, 1.0, v143
	v_rcp_f32_e32 v156, v143
	v_mul_f32_e32 v143, 0xbfb8aa3b, v127
	v_exp_f32_e32 v143, v143
	v_mov_b64_e32 v[146:147], s[8:9]
	v_pk_mul_f32 v[116:117], v[116:117], v[154:155] op_sel_hi:[1,0]
	v_mad_i64_i32 v[150:151], s[22:23], v142, s83, v[146:147]
	v_add_f32_e32 v143, 1.0, v143
	v_rcp_f32_e32 v157, v143
	s_nop 0
	v_pk_mul_f32 v[126:127], v[126:127], v[156:157]
	s_nop 0
	v_pk_mul_f32 v[118:119], v[118:119], v[126:127]
	v_pk_mul_f32 v[126:127], v[128:129], v[154:155] op_sel_hi:[1,0]
	v_cvt_pk_bf16_f32 v118, v118, v119
	v_mul_f32_e32 v128, 0xbfb8aa3b, v126
	v_mul_f32_e32 v129, 0xbfb8aa3b, v127
	v_exp_f32_e32 v128, v128
	v_exp_f32_e32 v129, v129
	v_add_f32_e32 v128, 1.0, v128
	v_add_f32_e32 v129, 1.0, v129
	v_rcp_f32_e32 v128, v128
	v_rcp_f32_e32 v129, v129
	s_nop 0
	v_pk_mul_f32 v[126:127], v[126:127], v[128:129]
	s_nop 0
	v_pk_mul_f32 v[120:121], v[120:121], v[126:127]
	v_mul_f32_e32 v126, 0xbfb8aa3b, v122
	v_mul_f32_e32 v127, 0xbfb8aa3b, v123
	v_exp_f32_e32 v126, v126
	v_exp_f32_e32 v127, v127
	v_cvt_pk_bf16_f32 v119, v120, v121
	v_add_f32_e32 v126, 1.0, v126
	v_add_f32_e32 v127, 1.0, v127
	v_rcp_f32_e32 v126, v126
	v_rcp_f32_e32 v127, v127
	s_nop 0
	v_pk_mul_f32 v[122:123], v[122:123], v[126:127]
	s_nop 0
	v_pk_mul_f32 v[122:123], v[114:115], v[122:123]
	v_pk_mul_f32 v[114:115], v[124:125], v[154:155] op_sel_hi:[1,0]
	v_cvt_pk_bf16_f32 v120, v122, v123
	v_mul_f32_e32 v124, 0xbfb8aa3b, v114
	v_mul_f32_e32 v125, 0xbfb8aa3b, v115
	v_exp_f32_e32 v124, v124
	v_exp_f32_e32 v125, v125
	v_add_f32_e32 v124, 1.0, v124
	v_add_f32_e32 v125, 1.0, v125
	v_rcp_f32_e32 v124, v124
	v_rcp_f32_e32 v125, v125
	s_nop 0
	v_pk_mul_f32 v[114:115], v[114:115], v[124:125]
	s_nop 0
	v_pk_mul_f32 v[116:117], v[116:117], v[114:115]
	v_lshlrev_b64 v[114:115], 1, v[148:149]
	v_lshl_add_u64 v[124:125], v[150:151], 0, v[114:115]
	v_cvt_pk_bf16_f32 v121, v116, v117
	global_store_dwordx4 v[124:125], v[118:121], off
	v_mov_b32_e32 v192, 0xbfb8aa3b
	v_ffbh_u32_e32 v180, v159
	v_min_u32_e32 v180, 32, v180
	v_lshlrev_b64 v[178:179], v180, v[158:159]
	v_min_u32_e32 v178, 1, v178
	v_or_b32_e32 v178, v179, v178
	v_cvt_f32_u32_e32 v178, v178
	v_sub_u32_e32 v179, 32, v180
	v_ldexp_f32 v178, v178, v179
	v_fmamk_f32 v178, v178, 0x31800000, v219
	v_cmp_gt_f32_e32 vcc, s86, v178
	v_mul_f32_e32 v179, 0x4b800000, v178
	s_nop 0
	v_cndmask_b32_e32 v178, v178, v179, vcc
	v_rsq_f32_e32 v178, v178
	v_or_b32_e32 v181, 16, v142
	v_mul_f32_e32 v179, 0x45800000, v178
	v_cndmask_b32_e32 v178, v178, v179, vcc
	v_mad_i64_i32 v[182:183], s[22:23], v181, s83, v[146:147]
	v_pk_mul_f32 v[110:111], v[110:111], v[178:179] op_sel_hi:[1,0]
	v_pk_mul_f32 v[112:113], v[112:113], v[178:179] op_sel_hi:[1,0]
	v_pk_mul_f32 v[106:107], v[106:107], v[178:179] op_sel_hi:[1,0]
	v_pk_mul_f32 v[108:109], v[108:109], v[178:179] op_sel_hi:[1,0]
	v_pk_mul_f32 v[102:103], v[102:103], v[178:179] op_sel_hi:[1,0]
	v_pk_mul_f32 v[104:105], v[104:105], v[178:179] op_sel_hi:[1,0]
	v_pk_mul_f32 v[98:99], v[98:99], v[178:179] op_sel_hi:[1,0]
	v_pk_mul_f32 v[100:101], v[100:101], v[178:179] op_sel_hi:[1,0]
	v_pk_mul_f32 v[188:189], v[110:111], v[192:193] op_sel_hi:[1,0]
	v_pk_mul_f32 v[190:191], v[112:113], v[192:193] op_sel_hi:[1,0]
	v_exp_f32_e32 v188, v188
	v_exp_f32_e32 v189, v189
	v_exp_f32_e32 v190, v190
	v_exp_f32_e32 v191, v191
	v_pk_add_f32 v[188:189], v[188:189], 1.0 op_sel_hi:[1,0]
	v_pk_add_f32 v[190:191], v[190:191], 1.0 op_sel_hi:[1,0]
	v_rcp_f32_e32 v188, v188
	v_rcp_f32_e32 v189, v189
	v_rcp_f32_e32 v190, v190
	v_rcp_f32_e32 v191, v191
	v_pk_mul_f32 v[110:111], v[110:111], v[188:189]
	v_pk_mul_f32 v[112:113], v[112:113], v[190:191]
	v_pk_mul_f32 v[102:103], v[102:103], v[110:111]
	v_pk_mul_f32 v[104:105], v[104:105], v[112:113]
	v_cvt_pk_bf16_f32 v184, v102, v103
	v_cvt_pk_bf16_f32 v185, v104, v105
	v_pk_mul_f32 v[188:189], v[106:107], v[192:193] op_sel_hi:[1,0]
	v_pk_mul_f32 v[190:191], v[108:109], v[192:193] op_sel_hi:[1,0]
	v_exp_f32_e32 v188, v188
	v_exp_f32_e32 v189, v189
	v_exp_f32_e32 v190, v190
	v_exp_f32_e32 v191, v191
	v_pk_add_f32 v[188:189], v[188:189], 1.0 op_sel_hi:[1,0]
	v_pk_add_f32 v[190:191], v[190:191], 1.0 op_sel_hi:[1,0]
	v_rcp_f32_e32 v188, v188
	v_rcp_f32_e32 v189, v189
	v_rcp_f32_e32 v190, v190
	v_rcp_f32_e32 v191, v191
	v_pk_mul_f32 v[106:107], v[106:107], v[188:189]
	v_pk_mul_f32 v[108:109], v[108:109], v[190:191]
	v_pk_mul_f32 v[98:99], v[98:99], v[106:107]
	v_pk_mul_f32 v[100:101], v[100:101], v[108:109]
	v_cvt_pk_bf16_f32 v186, v98, v99
	v_cvt_pk_bf16_f32 v187, v100, v101
	v_lshl_add_u64 v[182:183], v[182:183], 0, v[114:115]
	global_store_dwordx4 v[182:183], v[184:187], off
	v_ffbh_u32_e32 v180, v161
	v_min_u32_e32 v180, 32, v180
	v_lshlrev_b64 v[178:179], v180, v[160:161]
	v_min_u32_e32 v178, 1, v178
	v_or_b32_e32 v178, v179, v178
	v_cvt_f32_u32_e32 v178, v178
	v_sub_u32_e32 v179, 32, v180
	v_ldexp_f32 v178, v178, v179
	v_fmamk_f32 v178, v178, 0x31800000, v219
	v_cmp_gt_f32_e32 vcc, s86, v178
	v_mul_f32_e32 v179, 0x4b800000, v178
	s_nop 0
	v_cndmask_b32_e32 v178, v178, v179, vcc
	v_rsq_f32_e32 v178, v178
	v_or_b32_e32 v181, 32, v142
	v_mul_f32_e32 v179, 0x45800000, v178
	v_cndmask_b32_e32 v178, v178, v179, vcc
	v_mad_i64_i32 v[182:183], s[22:23], v181, s83, v[146:147]
	v_pk_mul_f32 v[94:95], v[94:95], v[178:179] op_sel_hi:[1,0]
	v_pk_mul_f32 v[96:97], v[96:97], v[178:179] op_sel_hi:[1,0]
	v_pk_mul_f32 v[90:91], v[90:91], v[178:179] op_sel_hi:[1,0]
	v_pk_mul_f32 v[92:93], v[92:93], v[178:179] op_sel_hi:[1,0]
	v_pk_mul_f32 v[86:87], v[86:87], v[178:179] op_sel_hi:[1,0]
	v_pk_mul_f32 v[88:89], v[88:89], v[178:179] op_sel_hi:[1,0]
	v_pk_mul_f32 v[82:83], v[82:83], v[178:179] op_sel_hi:[1,0]
	v_pk_mul_f32 v[84:85], v[84:85], v[178:179] op_sel_hi:[1,0]
	v_pk_mul_f32 v[188:189], v[94:95], v[192:193] op_sel_hi:[1,0]
	v_pk_mul_f32 v[190:191], v[96:97], v[192:193] op_sel_hi:[1,0]
	v_exp_f32_e32 v188, v188
	v_exp_f32_e32 v189, v189
	v_exp_f32_e32 v190, v190
	v_exp_f32_e32 v191, v191
	v_pk_add_f32 v[188:189], v[188:189], 1.0 op_sel_hi:[1,0]
	v_pk_add_f32 v[190:191], v[190:191], 1.0 op_sel_hi:[1,0]
	v_rcp_f32_e32 v188, v188
	v_rcp_f32_e32 v189, v189
	v_rcp_f32_e32 v190, v190
	v_rcp_f32_e32 v191, v191
	v_pk_mul_f32 v[94:95], v[94:95], v[188:189]
	v_pk_mul_f32 v[96:97], v[96:97], v[190:191]
	v_pk_mul_f32 v[86:87], v[86:87], v[94:95]
	v_pk_mul_f32 v[88:89], v[88:89], v[96:97]
	v_cvt_pk_bf16_f32 v184, v86, v87
	v_cvt_pk_bf16_f32 v185, v88, v89
	v_pk_mul_f32 v[188:189], v[90:91], v[192:193] op_sel_hi:[1,0]
	v_pk_mul_f32 v[190:191], v[92:93], v[192:193] op_sel_hi:[1,0]
	v_exp_f32_e32 v188, v188
	v_exp_f32_e32 v189, v189
	v_exp_f32_e32 v190, v190
	v_exp_f32_e32 v191, v191
	v_pk_add_f32 v[188:189], v[188:189], 1.0 op_sel_hi:[1,0]
	v_pk_add_f32 v[190:191], v[190:191], 1.0 op_sel_hi:[1,0]
	v_rcp_f32_e32 v188, v188
	v_rcp_f32_e32 v189, v189
	v_rcp_f32_e32 v190, v190
	v_rcp_f32_e32 v191, v191
	v_pk_mul_f32 v[90:91], v[90:91], v[188:189]
	v_pk_mul_f32 v[92:93], v[92:93], v[190:191]
	v_pk_mul_f32 v[82:83], v[82:83], v[90:91]
	v_pk_mul_f32 v[84:85], v[84:85], v[92:93]
	v_cvt_pk_bf16_f32 v186, v82, v83
	v_cvt_pk_bf16_f32 v187, v84, v85
	v_lshl_add_u64 v[182:183], v[182:183], 0, v[114:115]
	global_store_dwordx4 v[182:183], v[184:187], off
	v_ffbh_u32_e32 v180, v163
	v_min_u32_e32 v180, 32, v180
	v_lshlrev_b64 v[178:179], v180, v[162:163]
	v_min_u32_e32 v178, 1, v178
	v_or_b32_e32 v178, v179, v178
	v_cvt_f32_u32_e32 v178, v178
	v_sub_u32_e32 v179, 32, v180
	v_ldexp_f32 v178, v178, v179
	v_fmamk_f32 v178, v178, 0x31800000, v219
	v_cmp_gt_f32_e32 vcc, s86, v178
	v_mul_f32_e32 v179, 0x4b800000, v178
	s_nop 0
	v_cndmask_b32_e32 v178, v178, v179, vcc
	v_rsq_f32_e32 v178, v178
	v_or_b32_e32 v181, 48, v142
	v_mul_f32_e32 v179, 0x45800000, v178
	v_cndmask_b32_e32 v178, v178, v179, vcc
	v_mad_i64_i32 v[182:183], s[22:23], v181, s83, v[146:147]
	v_pk_mul_f32 v[78:79], v[78:79], v[178:179] op_sel_hi:[1,0]
	v_pk_mul_f32 v[80:81], v[80:81], v[178:179] op_sel_hi:[1,0]
	v_pk_mul_f32 v[74:75], v[74:75], v[178:179] op_sel_hi:[1,0]
	v_pk_mul_f32 v[76:77], v[76:77], v[178:179] op_sel_hi:[1,0]
	v_pk_mul_f32 v[70:71], v[70:71], v[178:179] op_sel_hi:[1,0]
	v_pk_mul_f32 v[72:73], v[72:73], v[178:179] op_sel_hi:[1,0]
	v_pk_mul_f32 v[66:67], v[66:67], v[178:179] op_sel_hi:[1,0]
	v_pk_mul_f32 v[68:69], v[68:69], v[178:179] op_sel_hi:[1,0]
	v_pk_mul_f32 v[188:189], v[78:79], v[192:193] op_sel_hi:[1,0]
	v_pk_mul_f32 v[190:191], v[80:81], v[192:193] op_sel_hi:[1,0]
	v_exp_f32_e32 v188, v188
	v_exp_f32_e32 v189, v189
	v_exp_f32_e32 v190, v190
	v_exp_f32_e32 v191, v191
	v_pk_add_f32 v[188:189], v[188:189], 1.0 op_sel_hi:[1,0]
	v_pk_add_f32 v[190:191], v[190:191], 1.0 op_sel_hi:[1,0]
	v_rcp_f32_e32 v188, v188
	v_rcp_f32_e32 v189, v189
	v_rcp_f32_e32 v190, v190
	v_rcp_f32_e32 v191, v191
	v_pk_mul_f32 v[78:79], v[78:79], v[188:189]
	v_pk_mul_f32 v[80:81], v[80:81], v[190:191]
	v_pk_mul_f32 v[70:71], v[70:71], v[78:79]
	v_pk_mul_f32 v[72:73], v[72:73], v[80:81]
	v_cvt_pk_bf16_f32 v184, v70, v71
	v_cvt_pk_bf16_f32 v185, v72, v73
	v_pk_mul_f32 v[188:189], v[74:75], v[192:193] op_sel_hi:[1,0]
	v_pk_mul_f32 v[190:191], v[76:77], v[192:193] op_sel_hi:[1,0]
	v_exp_f32_e32 v188, v188
	v_exp_f32_e32 v189, v189
	v_exp_f32_e32 v190, v190
	v_exp_f32_e32 v191, v191
	v_pk_add_f32 v[188:189], v[188:189], 1.0 op_sel_hi:[1,0]
	v_pk_add_f32 v[190:191], v[190:191], 1.0 op_sel_hi:[1,0]
	v_rcp_f32_e32 v188, v188
	v_rcp_f32_e32 v189, v189
	v_rcp_f32_e32 v190, v190
	v_rcp_f32_e32 v191, v191
	v_pk_mul_f32 v[74:75], v[74:75], v[188:189]
	v_pk_mul_f32 v[76:77], v[76:77], v[190:191]
	v_pk_mul_f32 v[66:67], v[66:67], v[74:75]
	v_pk_mul_f32 v[68:69], v[68:69], v[76:77]
	v_cvt_pk_bf16_f32 v186, v66, v67
	v_cvt_pk_bf16_f32 v187, v68, v69
	v_lshl_add_u64 v[182:183], v[182:183], 0, v[114:115]
	global_store_dwordx4 v[182:183], v[184:187], off
	v_ffbh_u32_e32 v180, v165
	v_min_u32_e32 v180, 32, v180
	v_lshlrev_b64 v[178:179], v180, v[164:165]
	v_min_u32_e32 v178, 1, v178
	v_or_b32_e32 v178, v179, v178
	v_cvt_f32_u32_e32 v178, v178
	v_sub_u32_e32 v179, 32, v180
	v_ldexp_f32 v178, v178, v179
	v_fmamk_f32 v178, v178, 0x31800000, v219
	v_cmp_gt_f32_e32 vcc, s86, v178
	v_mul_f32_e32 v179, 0x4b800000, v178
	s_nop 0
	v_cndmask_b32_e32 v178, v178, v179, vcc
	v_rsq_f32_e32 v178, v178
	v_add_u32_e32 v181, 0x80, v142
	v_mul_f32_e32 v179, 0x45800000, v178
	v_cndmask_b32_e32 v178, v178, v179, vcc
	v_mad_i64_i32 v[182:183], s[22:23], v181, s83, v[146:147]
	v_pk_mul_f32 v[62:63], v[62:63], v[178:179] op_sel_hi:[1,0]
	v_pk_mul_f32 v[64:65], v[64:65], v[178:179] op_sel_hi:[1,0]
	v_pk_mul_f32 v[58:59], v[58:59], v[178:179] op_sel_hi:[1,0]
	v_pk_mul_f32 v[60:61], v[60:61], v[178:179] op_sel_hi:[1,0]
	v_pk_mul_f32 v[54:55], v[54:55], v[178:179] op_sel_hi:[1,0]
	v_pk_mul_f32 v[56:57], v[56:57], v[178:179] op_sel_hi:[1,0]
	v_pk_mul_f32 v[50:51], v[50:51], v[178:179] op_sel_hi:[1,0]
	v_pk_mul_f32 v[52:53], v[52:53], v[178:179] op_sel_hi:[1,0]
	v_pk_mul_f32 v[188:189], v[62:63], v[192:193] op_sel_hi:[1,0]
	v_pk_mul_f32 v[190:191], v[64:65], v[192:193] op_sel_hi:[1,0]
	v_exp_f32_e32 v188, v188
	v_exp_f32_e32 v189, v189
	v_exp_f32_e32 v190, v190
	v_exp_f32_e32 v191, v191
	v_pk_add_f32 v[188:189], v[188:189], 1.0 op_sel_hi:[1,0]
	v_pk_add_f32 v[190:191], v[190:191], 1.0 op_sel_hi:[1,0]
	v_rcp_f32_e32 v188, v188
	v_rcp_f32_e32 v189, v189
	v_rcp_f32_e32 v190, v190
	v_rcp_f32_e32 v191, v191
	v_pk_mul_f32 v[62:63], v[62:63], v[188:189]
	v_pk_mul_f32 v[64:65], v[64:65], v[190:191]
	v_pk_mul_f32 v[54:55], v[54:55], v[62:63]
	v_pk_mul_f32 v[56:57], v[56:57], v[64:65]
	v_cvt_pk_bf16_f32 v184, v54, v55
	v_cvt_pk_bf16_f32 v185, v56, v57
	v_pk_mul_f32 v[188:189], v[58:59], v[192:193] op_sel_hi:[1,0]
	v_pk_mul_f32 v[190:191], v[60:61], v[192:193] op_sel_hi:[1,0]
	v_exp_f32_e32 v188, v188
	v_exp_f32_e32 v189, v189
	v_exp_f32_e32 v190, v190
	v_exp_f32_e32 v191, v191
	v_pk_add_f32 v[188:189], v[188:189], 1.0 op_sel_hi:[1,0]
	v_pk_add_f32 v[190:191], v[190:191], 1.0 op_sel_hi:[1,0]
	v_rcp_f32_e32 v188, v188
	v_rcp_f32_e32 v189, v189
	v_rcp_f32_e32 v190, v190
	v_rcp_f32_e32 v191, v191
	v_pk_mul_f32 v[58:59], v[58:59], v[188:189]
	v_pk_mul_f32 v[60:61], v[60:61], v[190:191]
	v_pk_mul_f32 v[50:51], v[50:51], v[58:59]
	v_pk_mul_f32 v[52:53], v[52:53], v[60:61]
	v_cvt_pk_bf16_f32 v186, v50, v51
	v_cvt_pk_bf16_f32 v187, v52, v53
	v_lshl_add_u64 v[182:183], v[182:183], 0, v[114:115]
	global_store_dwordx4 v[182:183], v[184:187], off
	v_ffbh_u32_e32 v180, v167
	v_min_u32_e32 v180, 32, v180
	v_lshlrev_b64 v[178:179], v180, v[166:167]
	v_min_u32_e32 v178, 1, v178
	v_or_b32_e32 v178, v179, v178
	v_cvt_f32_u32_e32 v178, v178
	v_sub_u32_e32 v179, 32, v180
	v_ldexp_f32 v178, v178, v179
	v_fmamk_f32 v178, v178, 0x31800000, v219
	v_cmp_gt_f32_e32 vcc, s86, v178
	v_mul_f32_e32 v179, 0x4b800000, v178
	s_nop 0
	v_cndmask_b32_e32 v178, v178, v179, vcc
	v_rsq_f32_e32 v178, v178
	v_add_u32_e32 v181, 0x90, v142
	v_mul_f32_e32 v179, 0x45800000, v178
	v_cndmask_b32_e32 v178, v178, v179, vcc
	v_mad_i64_i32 v[182:183], s[22:23], v181, s83, v[146:147]
	v_pk_mul_f32 v[46:47], v[46:47], v[178:179] op_sel_hi:[1,0]
	v_pk_mul_f32 v[48:49], v[48:49], v[178:179] op_sel_hi:[1,0]
	v_pk_mul_f32 v[42:43], v[42:43], v[178:179] op_sel_hi:[1,0]
	v_pk_mul_f32 v[44:45], v[44:45], v[178:179] op_sel_hi:[1,0]
	v_pk_mul_f32 v[38:39], v[38:39], v[178:179] op_sel_hi:[1,0]
	v_pk_mul_f32 v[40:41], v[40:41], v[178:179] op_sel_hi:[1,0]
	v_pk_mul_f32 v[34:35], v[34:35], v[178:179] op_sel_hi:[1,0]
	v_pk_mul_f32 v[36:37], v[36:37], v[178:179] op_sel_hi:[1,0]
	v_pk_mul_f32 v[188:189], v[46:47], v[192:193] op_sel_hi:[1,0]
	v_pk_mul_f32 v[190:191], v[48:49], v[192:193] op_sel_hi:[1,0]
	v_exp_f32_e32 v188, v188
	v_exp_f32_e32 v189, v189
	v_exp_f32_e32 v190, v190
	v_exp_f32_e32 v191, v191
	v_pk_add_f32 v[188:189], v[188:189], 1.0 op_sel_hi:[1,0]
	v_pk_add_f32 v[190:191], v[190:191], 1.0 op_sel_hi:[1,0]
	v_rcp_f32_e32 v188, v188
	v_rcp_f32_e32 v189, v189
	v_rcp_f32_e32 v190, v190
	v_rcp_f32_e32 v191, v191
	v_pk_mul_f32 v[46:47], v[46:47], v[188:189]
	v_pk_mul_f32 v[48:49], v[48:49], v[190:191]
	v_pk_mul_f32 v[38:39], v[38:39], v[46:47]
	v_pk_mul_f32 v[40:41], v[40:41], v[48:49]
	v_cvt_pk_bf16_f32 v184, v38, v39
	v_cvt_pk_bf16_f32 v185, v40, v41
	v_pk_mul_f32 v[188:189], v[42:43], v[192:193] op_sel_hi:[1,0]
	v_pk_mul_f32 v[190:191], v[44:45], v[192:193] op_sel_hi:[1,0]
	v_exp_f32_e32 v188, v188
	v_exp_f32_e32 v189, v189
	v_exp_f32_e32 v190, v190
	v_exp_f32_e32 v191, v191
	v_pk_add_f32 v[188:189], v[188:189], 1.0 op_sel_hi:[1,0]
	v_pk_add_f32 v[190:191], v[190:191], 1.0 op_sel_hi:[1,0]
	v_rcp_f32_e32 v188, v188
	v_rcp_f32_e32 v189, v189
	v_rcp_f32_e32 v190, v190
	v_rcp_f32_e32 v191, v191
	v_pk_mul_f32 v[42:43], v[42:43], v[188:189]
	v_pk_mul_f32 v[44:45], v[44:45], v[190:191]
	v_pk_mul_f32 v[34:35], v[34:35], v[42:43]
	v_pk_mul_f32 v[36:37], v[36:37], v[44:45]
	v_cvt_pk_bf16_f32 v186, v34, v35
	v_cvt_pk_bf16_f32 v187, v36, v37
	v_lshl_add_u64 v[182:183], v[182:183], 0, v[114:115]
	global_store_dwordx4 v[182:183], v[184:187], off
	v_ffbh_u32_e32 v180, v169
	v_min_u32_e32 v180, 32, v180
	v_lshlrev_b64 v[178:179], v180, v[168:169]
	v_min_u32_e32 v178, 1, v178
	v_or_b32_e32 v178, v179, v178
	v_cvt_f32_u32_e32 v178, v178
	v_sub_u32_e32 v179, 32, v180
	v_ldexp_f32 v178, v178, v179
	v_fmamk_f32 v178, v178, 0x31800000, v219
	v_cmp_gt_f32_e32 vcc, s86, v178
	v_mul_f32_e32 v179, 0x4b800000, v178
	s_nop 0
	v_cndmask_b32_e32 v178, v178, v179, vcc
	v_rsq_f32_e32 v178, v178
	v_add_u32_e32 v181, 0xa0, v142
	v_mul_f32_e32 v179, 0x45800000, v178
	v_cndmask_b32_e32 v178, v178, v179, vcc
	v_mad_i64_i32 v[182:183], s[22:23], v181, s83, v[146:147]
	v_pk_mul_f32 v[30:31], v[30:31], v[178:179] op_sel_hi:[1,0]
	v_pk_mul_f32 v[32:33], v[32:33], v[178:179] op_sel_hi:[1,0]
	v_pk_mul_f32 v[26:27], v[26:27], v[178:179] op_sel_hi:[1,0]
	v_pk_mul_f32 v[28:29], v[28:29], v[178:179] op_sel_hi:[1,0]
	v_pk_mul_f32 v[22:23], v[22:23], v[178:179] op_sel_hi:[1,0]
	v_pk_mul_f32 v[24:25], v[24:25], v[178:179] op_sel_hi:[1,0]
	v_pk_mul_f32 v[18:19], v[18:19], v[178:179] op_sel_hi:[1,0]
	v_pk_mul_f32 v[20:21], v[20:21], v[178:179] op_sel_hi:[1,0]
	v_pk_mul_f32 v[188:189], v[30:31], v[192:193] op_sel_hi:[1,0]
	v_pk_mul_f32 v[190:191], v[32:33], v[192:193] op_sel_hi:[1,0]
	v_exp_f32_e32 v188, v188
	v_exp_f32_e32 v189, v189
	v_exp_f32_e32 v190, v190
	v_exp_f32_e32 v191, v191
	v_pk_add_f32 v[188:189], v[188:189], 1.0 op_sel_hi:[1,0]
	v_pk_add_f32 v[190:191], v[190:191], 1.0 op_sel_hi:[1,0]
	v_rcp_f32_e32 v188, v188
	v_rcp_f32_e32 v189, v189
	v_rcp_f32_e32 v190, v190
	v_rcp_f32_e32 v191, v191
	v_pk_mul_f32 v[30:31], v[30:31], v[188:189]
	v_pk_mul_f32 v[32:33], v[32:33], v[190:191]
	v_pk_mul_f32 v[22:23], v[22:23], v[30:31]
	v_pk_mul_f32 v[24:25], v[24:25], v[32:33]
	v_cvt_pk_bf16_f32 v184, v22, v23
	v_cvt_pk_bf16_f32 v185, v24, v25
	v_pk_mul_f32 v[188:189], v[26:27], v[192:193] op_sel_hi:[1,0]
	v_pk_mul_f32 v[190:191], v[28:29], v[192:193] op_sel_hi:[1,0]
	v_exp_f32_e32 v188, v188
	v_exp_f32_e32 v189, v189
	v_exp_f32_e32 v190, v190
	v_exp_f32_e32 v191, v191
	v_pk_add_f32 v[188:189], v[188:189], 1.0 op_sel_hi:[1,0]
	v_pk_add_f32 v[190:191], v[190:191], 1.0 op_sel_hi:[1,0]
	v_rcp_f32_e32 v188, v188
	v_rcp_f32_e32 v189, v189
	v_rcp_f32_e32 v190, v190
	v_rcp_f32_e32 v191, v191
	v_pk_mul_f32 v[26:27], v[26:27], v[188:189]
	v_pk_mul_f32 v[28:29], v[28:29], v[190:191]
	v_pk_mul_f32 v[18:19], v[18:19], v[26:27]
	v_pk_mul_f32 v[20:21], v[20:21], v[28:29]
	v_cvt_pk_bf16_f32 v186, v18, v19
	v_cvt_pk_bf16_f32 v187, v20, v21
	v_lshl_add_u64 v[182:183], v[182:183], 0, v[114:115]
	global_store_dwordx4 v[182:183], v[184:187], off
	v_ffbh_u32_e32 v180, v171
	v_min_u32_e32 v180, 32, v180
	v_lshlrev_b64 v[178:179], v180, v[170:171]
	v_min_u32_e32 v178, 1, v178
	v_or_b32_e32 v178, v179, v178
	v_cvt_f32_u32_e32 v178, v178
	v_sub_u32_e32 v179, 32, v180
	v_ldexp_f32 v178, v178, v179
	v_fmamk_f32 v178, v178, 0x31800000, v219
	v_cmp_gt_f32_e32 vcc, s86, v178
	v_mul_f32_e32 v179, 0x4b800000, v178
	s_nop 0
	v_cndmask_b32_e32 v178, v178, v179, vcc
	v_rsq_f32_e32 v178, v178
	v_add_u32_e32 v181, 0xb0, v142
	v_mul_f32_e32 v179, 0x45800000, v178
	v_cndmask_b32_e32 v178, v178, v179, vcc
	v_mad_i64_i32 v[182:183], s[22:23], v181, s83, v[146:147]
	s_andn2_b64 vcc, exec, s[2:3]
	v_pk_mul_f32 v[14:15], v[14:15], v[178:179] op_sel_hi:[1,0]
	v_pk_mul_f32 v[16:17], v[16:17], v[178:179] op_sel_hi:[1,0]
	v_pk_mul_f32 v[10:11], v[10:11], v[178:179] op_sel_hi:[1,0]
	v_pk_mul_f32 v[12:13], v[12:13], v[178:179] op_sel_hi:[1,0]
	v_pk_mul_f32 v[6:7], v[6:7], v[178:179] op_sel_hi:[1,0]
	v_pk_mul_f32 v[8:9], v[8:9], v[178:179] op_sel_hi:[1,0]
	v_pk_mul_f32 v[2:3], v[2:3], v[178:179] op_sel_hi:[1,0]
	v_pk_mul_f32 v[4:5], v[4:5], v[178:179] op_sel_hi:[1,0]
	s_mov_b64 s[22:23], -1
	v_pk_mul_f32 v[188:189], v[14:15], v[192:193] op_sel_hi:[1,0]
	v_pk_mul_f32 v[190:191], v[16:17], v[192:193] op_sel_hi:[1,0]
	v_exp_f32_e32 v188, v188
	v_exp_f32_e32 v189, v189
	v_exp_f32_e32 v190, v190
	v_exp_f32_e32 v191, v191
	v_pk_add_f32 v[188:189], v[188:189], 1.0 op_sel_hi:[1,0]
	v_pk_add_f32 v[190:191], v[190:191], 1.0 op_sel_hi:[1,0]
	v_rcp_f32_e32 v188, v188
	v_rcp_f32_e32 v189, v189
	v_rcp_f32_e32 v190, v190
	v_rcp_f32_e32 v191, v191
	v_pk_mul_f32 v[14:15], v[14:15], v[188:189]
	v_pk_mul_f32 v[16:17], v[16:17], v[190:191]
	v_pk_mul_f32 v[6:7], v[6:7], v[14:15]
	v_pk_mul_f32 v[8:9], v[8:9], v[16:17]
	v_cvt_pk_bf16_f32 v184, v6, v7
	v_cvt_pk_bf16_f32 v185, v8, v9
	v_pk_mul_f32 v[188:189], v[10:11], v[192:193] op_sel_hi:[1,0]
	v_pk_mul_f32 v[190:191], v[12:13], v[192:193] op_sel_hi:[1,0]
	v_exp_f32_e32 v188, v188
	v_exp_f32_e32 v189, v189
	v_exp_f32_e32 v190, v190
	v_exp_f32_e32 v191, v191
	v_pk_add_f32 v[188:189], v[188:189], 1.0 op_sel_hi:[1,0]
	v_pk_add_f32 v[190:191], v[190:191], 1.0 op_sel_hi:[1,0]
	v_rcp_f32_e32 v188, v188
	v_rcp_f32_e32 v189, v189
	v_rcp_f32_e32 v190, v190
	v_rcp_f32_e32 v191, v191
	v_pk_mul_f32 v[10:11], v[10:11], v[188:189]
	v_pk_mul_f32 v[12:13], v[12:13], v[190:191]
	v_pk_mul_f32 v[2:3], v[2:3], v[10:11]
	v_pk_mul_f32 v[4:5], v[4:5], v[12:13]
	v_cvt_pk_bf16_f32 v186, v2, v3
	v_cvt_pk_bf16_f32 v187, v4, v5
	v_lshl_add_u64 v[182:183], v[182:183], 0, v[114:115]
	global_store_dwordx4 v[182:183], v[184:187], off
	s_cbranch_vccnz .LBB0_1176
	s_andn2_b64 vcc, exec, s[6:7]
	s_cbranch_vccnz .LBB0_1175
	s_barrier
	s_branch .LBB0_1175
